# grid barrier: follower blocks poll the top-level generation word directly (one hop less)
# speedup vs baseline: 1.0231x; 1.0001x over previous
.LBB0_1934:
	s_or_b64 exec, exec, s[2:3]
	v_cvt_f32_u32_e32 v5, v3
	s_waitcnt vmcnt(0)
	v_readfirstlane_b32 s2, v4
	v_sub_u32_e32 v4, 0, v3
	v_rcp_iflag_f32_e32 v5, v5
	v_add_u32_e32 v6, s2, v0
	v_mul_f32_e32 v5, 0x4f7ffffe, v5
	v_cvt_u32_f32_e32 v5, v5
	v_mul_lo_u32 v0, v4, v5
	v_mul_hi_u32 v0, v5, v0
	v_add_u32_e32 v0, v5, v0
	v_mul_hi_u32 v0, v6, v0
	v_mul_lo_u32 v4, v0, v3
	v_sub_u32_e32 v4, v6, v4
	v_add_u32_e32 v5, 1, v0
	v_cmp_ge_u32_e32 vcc, v4, v3
	s_nop 1
	v_cndmask_b32_e32 v0, v0, v5, vcc
	v_sub_u32_e32 v5, v4, v3
	v_cndmask_b32_e32 v4, v4, v5, vcc
	v_add_u32_e32 v5, 1, v0
	v_cmp_ge_u32_e32 vcc, v4, v3
	v_add_u32_e32 v4, 1, v6
	s_nop 0
	v_cndmask_b32_e32 v0, v0, v5, vcc
	v_mul_lo_u32 v5, v3, v0
	v_add_u32_e32 v3, v5, v3
	v_cmp_ne_u32_e32 vcc, v4, v3
	s_and_saveexec_b64 s[2:3], vcc
	s_xor_b64 s[2:3], exec, s[2:3]
	s_cbranch_execz .LBB0_1948
	v_readlane_b32 s4, v254, 29
	v_readlane_b32 s5, v254, 30
	s_waitcnt lgkmcnt(0)
	s_nop 3
	global_load_dword v2, v1, s[4:5] sc1
	s_waitcnt vmcnt(0)
	v_cmp_eq_u32_e32 vcc, v2, v0
	s_and_saveexec_b64 s[4:5], vcc
	s_cbranch_execz .LBB0_1947
	s_mov_b32 s17, 1
	s_mov_b64 s[6:7], 0
	s_branch .LBB0_1938
